# pooling items rebalanced between phases: 560 (was 384) in the S3 work queue, 2 per workgroup left in S4
# baseline (speedup 1.0000x reference)
; DEV unsigned xb_ld(unsigned* p)              { return __hip_atomic_load(p, __ATOMIC_RELAXED, __HIP_MEMORY_SCOPE_AGENT); }
; DEV void xcd_barrier_complete(unsigned* bar, unsigned x, unsigned& nloc, unsigned& nx) {
;     ...
;         for (unsigned j = 0; j < 16; ++j) { const unsigned c = xb_ld(&bar[XB_XCNT(j)]); sum += c; cnt += (c > 0u) ? 1u : 0u; mine = (j == x) ? c : mine; }
; __global__ void __launch_bounds__(NTHR, 2) fwd_megakernel(Args args) {
;     ...
;     F.A = (bf16_t*)(F.ws + WS_A); F.Y = (bf16_t*)(F.ws + WS_Z); F.XB = (bf16_t*)(F.ws + WS_Y);     F.Z = (bf16_t*)(F.ws + WS_Z); F.MIX = (bf16_t*)(F.ws + WS_MIX); F.H = (bf16_t*)(F.ws + WS_H);
;     F.CL = (float*)(F.ws + WS_CL); F.NL = (float*)(F.ws + WS_NL); F.AL = (float*)(F.ws + WS_SC); F.BE = F.AL + 16 * NCH; F.MS = F.BE + 16 * NCH;
;     F.MOD = (float*)(F.ws + WS_MOD); F.CTXR = (float*)(F.ws + WS_CTXR); F.ROPE = (float*)(F.ws + WS_ROPE);
.LBB0_216:
	s_add_u32 s78, s12, 0x8200000
	s_addc_u32 s79, s13, 0
	s_add_u32 s0, s12, 0x4100000
	s_addc_u32 s1, s13, 0
	s_add_u32 s80, s12, 0x12480000
	v_writelane_b32 v242, s0, 35
	s_addc_u32 s81, s13, 0
	v_mov_b32_e32 v69, v188
	v_writelane_b32 v242, s1, 36
	s_add_u32 s0, s12, 0x1c380000
	s_addc_u32 s1, s13, 0
	v_writelane_b32 v242, s0, 37
	v_mov_b32_e32 v191, 1
	v_mov_b32_e32 v192, 0x3ecc95a3
	v_writelane_b32 v242, s1, 38
	s_add_u32 s0, s12, 0x1e400000
	s_addc_u32 s1, s13, 0
	s_add_u32 s82, s12, 0x1e482000
	s_addc_u32 s83, s13, 0
	s_add_u32 s84, s12, 0x1e484080
	v_writelane_b32 v242, s0, 39
	s_addc_u32 s85, s13, 0
	v_mov_b32_e32 v193, 0xff800000
	v_writelane_b32 v242, s1, 40
	s_add_u32 s0, s12, 0x1e486100
	s_addc_u32 s1, s13, 0
	s_add_u32 s86, s12, 0x1e6dc200
	s_addc_u32 s87, s13, 0
	s_add_u32 s88, s12, 0x1e6dc400
	s_addc_u32 s89, s13, 0
	s_add_u32 s90, s12, 0x1e6dc500
	s_addc_u32 s91, s13, 0
	s_add_u32 s92, s12, 0x1e6dc600
	s_addc_u32 s93, s13, 0
	s_add_u32 s94, s12, 0x1e6dc700
	s_addc_u32 s95, s13, 0
	s_add_u32 s96, s12, 0x1e6dc800
	s_addc_u32 s97, s13, 0
	v_writelane_b32 v242, s0, 41
	s_add_u32 s34, s12, 0x1e6dc900
	s_addc_u32 s35, s13, 0
	v_writelane_b32 v242, s1, 42
	s_mul_i32 s0, s15, s14
	s_mul_i32 s57, s0, s50
	s_add_u32 s0, s12, 0x1e6dca00
	s_addc_u32 s1, s13, 0
	v_writelane_b32 v242, s0, 43
	v_mov_b32_e32 v194, 0x358637bd
	v_mov_b32_e32 v140, 1.0
	v_writelane_b32 v242, s1, 44
	s_add_u32 s0, s12, 0x1e6dcb00
	s_addc_u32 s1, s13, 0
	v_writelane_b32 v242, s0, 45
	v_mov_b64_e32 v[142:143], 0x4ff
	v_mov_b32_e32 v195, 0x7f800000
	v_writelane_b32 v242, s1, 46
	s_add_u32 s0, s12, 0x1e6dcc00
	s_addc_u32 s1, s13, 0
	v_writelane_b32 v242, s0, 47
	v_mov_b32_e32 v196, 0x7fc00000
	v_mov_b32_e32 v144, 0
	v_writelane_b32 v242, s1, 48
	s_add_u32 s0, s12, 0x1e6dcd00
	s_addc_u32 s1, s13, 0
	v_writelane_b32 v242, s0, 49
	v_mov_b64_e32 v[146:147], 0x1ff
	v_mov_b64_e32 v[148:149], 0xaff
	v_writelane_b32 v242, s1, 50
	s_add_u32 s0, s12, 0x1e6dce00
	s_addc_u32 s1, s13, 0
	v_writelane_b32 v242, s0, 51
	v_mov_b32_e32 v197, 0x1600
	s_mov_b32 s22, 0x10000
	v_writelane_b32 v242, s1, 52
	s_add_u32 s0, s12, 0x1e6dcf00
	s_addc_u32 s1, s13, 0
	v_writelane_b32 v242, s0, 53
	s_movk_i32 s53, 0x1400
	s_mov_b32 s52, 0x800000
	v_writelane_b32 v242, s1, 54
	s_add_u32 s0, s12, 0x1e6dd000
	s_addc_u32 s1, s13, 0
	v_writelane_b32 v242, s0, 55
	s_mov_b32 s30, 0
	s_mov_b32 s61, 0
	v_writelane_b32 v242, s1, 56
	s_add_u32 s0, s12, 0x1e6dd100
	s_addc_u32 s1, s13, 0
	v_writelane_b32 v242, s0, 57
	s_nop 1
	v_writelane_b32 v242, s1, 58
	s_add_u32 s0, s12, 0x1e6dd200
	s_addc_u32 s1, s13, 0
	v_writelane_b32 v242, s0, 59
	s_nop 1
	v_writelane_b32 v242, s1, 60
	s_add_u32 s0, s12, 0x1e6dd300
	s_addc_u32 s1, s13, 0
	v_writelane_b32 v242, s0, 61
	s_cmp_eq_u32 s33, 15
	s_nop 0
	v_writelane_b32 v242, s1, 62
	s_cselect_b64 s[0:1], -1, 0
	v_writelane_b32 v242, s0, 63
	s_cmp_eq_u32 s33, 14
	s_nop 0
	v_writelane_b32 v241, s1, 0
	s_cselect_b64 s[0:1], -1, 0
	v_writelane_b32 v241, s0, 1
	s_cmp_eq_u32 s33, 13
	s_nop 0
	v_writelane_b32 v241, s1, 2
	s_cselect_b64 s[0:1], -1, 0
	v_writelane_b32 v241, s0, 3
	s_cmp_eq_u32 s33, 12
	s_nop 0
	v_writelane_b32 v241, s1, 4
	s_cselect_b64 s[0:1], -1, 0
	v_writelane_b32 v241, s0, 5
	s_cmp_eq_u32 s33, 11
	s_nop 0
	v_writelane_b32 v241, s1, 6
	s_cselect_b64 s[0:1], -1, 0
	v_writelane_b32 v241, s0, 7
	s_cmp_eq_u32 s33, 10
	s_nop 0
	v_writelane_b32 v241, s1, 8
	s_cselect_b64 s[0:1], -1, 0
	v_writelane_b32 v241, s0, 9
	s_cmp_eq_u32 s33, 9
	s_nop 0
	v_writelane_b32 v241, s1, 10
	s_cselect_b64 s[0:1], -1, 0
	v_writelane_b32 v241, s0, 11
	s_cmp_eq_u32 s33, 8
	s_nop 0
	v_writelane_b32 v241, s1, 12
	s_cselect_b64 s[0:1], -1, 0
	v_writelane_b32 v241, s0, 13
	s_cmp_eq_u32 s33, 7
	s_nop 0
	v_writelane_b32 v241, s1, 14
	s_cselect_b64 s[0:1], -1, 0
	v_writelane_b32 v241, s0, 15
	s_cmp_eq_u32 s33, 6
	s_nop 0
	v_writelane_b32 v241, s1, 16
	s_cselect_b64 s[0:1], -1, 0
	v_writelane_b32 v241, s0, 17
	s_cmp_eq_u32 s33, 5
	s_nop 0
	v_writelane_b32 v241, s1, 18
	s_cselect_b64 s[0:1], -1, 0
	v_writelane_b32 v241, s0, 19
	s_cmp_eq_u32 s33, 4
	s_nop 0
	v_writelane_b32 v241, s1, 20
	s_cselect_b64 s[0:1], -1, 0
	v_writelane_b32 v241, s0, 21
	s_cmp_eq_u32 s33, 3
	s_nop 0
	v_writelane_b32 v241, s1, 22
	s_cselect_b64 s[0:1], -1, 0
	v_writelane_b32 v241, s0, 23
	s_cmp_eq_u32 s33, 2
	s_nop 0
	v_writelane_b32 v241, s1, 24
	s_cselect_b64 s[0:1], -1, 0
	v_writelane_b32 v241, s0, 25
	s_cmp_eq_u32 s33, 1
	s_nop 0
	v_writelane_b32 v241, s1, 26
	s_cselect_b64 s[0:1], -1, 0
	v_writelane_b32 v241, s0, 27
	s_cmp_eq_u32 s33, 0
	s_nop 0
	v_writelane_b32 v241, s1, 28
	s_cselect_b64 s[0:1], -1, 0
	v_writelane_b32 v241, s0, 29
	s_nop 1
	v_writelane_b32 v241, s1, 30
	s_lshl_b32 s0, s51, 2
	s_add_u32 s0, s20, s0
	s_addc_u32 s1, s21, 0
	s_add_u32 s2, s0, 0x1400
	s_addc_u32 s3, s1, 0
	v_writelane_b32 v241, s2, 31
	s_nop 1
	v_writelane_b32 v241, s3, 32
	s_add_u32 s2, s0, 0x2400
	s_addc_u32 s3, s1, 0
	v_writelane_b32 v241, s2, 33
	s_nop 1
	v_writelane_b32 v241, s3, 34
	s_add_u32 s2, s12, 0x1e6df400
	s_addc_u32 s3, s13, 0
	v_writelane_b32 v241, s2, 35
	s_nop 1
	v_writelane_b32 v241, s3, 36
	s_add_u32 s2, s12, 0x1e6df500
	s_addc_u32 s3, s13, 0
	v_writelane_b32 v241, s2, 37
	s_add_u32 s0, s0, 0x3800
	s_addc_u32 s1, s1, 0
	v_writelane_b32 v241, s3, 38
	v_writelane_b32 v241, s0, 39
	s_cmpk_lt_i32 s56, 0xa0
	s_cselect_b64 s[2:3], -1, 0
	v_writelane_b32 v241, s1, 40
	s_mul_hi_i32 s0, s56, 0x66666667
	s_lshr_b32 s1, s0, 31
	s_ashr_i32 s0, s0, 4
	v_writelane_b32 v241, s2, 41
	s_add_i32 s0, s0, s1
	s_lshl_b32 s1, s0, 2
	v_writelane_b32 v241, s3, 42
	s_mulk_i32 s0, 0xffd8
	s_lshl_b32 s2, s33, 4
	s_add_i32 s0, s0, s56
; __global__ void __launch_bounds__(NTHR, 2) fwd_megakernel(Args args) {
;     ...
;         if (F.bid >= 16) pool_phase(F, l, 384 + F.bid - 16, F.G - 16);
	s_add_i32 s1, s1, s2
	s_and_b32 s3, s56, 3
	s_or_b32 s1, s1, s3
	s_ashr_i32 s0, s0, 2
	v_writelane_b32 v241, s1, 43
	s_cmpk_lt_i32 s55, 0x500
	v_writelane_b32 v241, s0, 44
	s_cselect_b64 s[0:1], -1, 0
	v_writelane_b32 v241, s0, 45
	s_ashr_i32 s54, s55, 31
	s_nop 0
	v_writelane_b32 v241, s1, 46
	s_lshr_b32 s0, s54, 29
	s_add_i32 s1, s55, s0
	s_or_b32 s0, s2, s3
	s_ashr_i32 s4, s1, 3
	v_writelane_b32 v241, s0, 47
	s_ashr_i32 s0, s14, 31
	s_cmp_lt_i32 s56, 37
	v_writelane_b32 v241, s0, 48
	s_cselect_b64 s[6:7], -1, 0
	v_writelane_b32 v241, s6, 49
	s_cmpk_lg_i32 s14, 0x100
	s_nop 0
	v_writelane_b32 v241, s7, 50
	s_cselect_b64 s[6:7], -1, 0
	v_writelane_b32 v241, s6, 51
	s_cmpk_lt_i32 s55, 0x128
	s_nop 0
	v_writelane_b32 v241, s7, 52
	s_cselect_b64 s[6:7], -1, 0
	v_writelane_b32 v241, s6, 53
	s_ashr_i32 s0, s55, 3
	s_and_b32 s5, s0, -8
	v_writelane_b32 v241, s7, 54
	s_and_b32 s6, s55, 7
	s_or_b32 s9, s5, s6
	s_cmp_lt_i32 s9, 37
	v_writelane_b32 v241, s6, 55
	s_cselect_b64 s[6:7], -1, 0
	v_writelane_b32 v241, s6, 56
	s_lshl_b32 s5, s0, 6
	s_and_b32 s5, s5, 0xc0
	v_writelane_b32 v241, s7, 57
	s_bfe_u32 s6, s0, 0x10002
	s_mulk_i32 s6, 0x4100
	s_or_b32 s5, s6, s5
	s_cmpk_lt_i32 s55, 0x410
	v_writelane_b32 v241, s5, 58
	s_cselect_b64 s[6:7], -1, 0
	s_lshl_b32 s5, s14, 4
	v_writelane_b32 v241, s6, 59
	s_add_i32 s5, s55, s5
	s_nop 0
	v_writelane_b32 v241, s7, 60
	s_add_i32 s6, s5, 0xfffffbf0
	s_addk_i32 s5, 0xf7e0
	s_add_u32 s7, s12, 0x1e6df600
	v_writelane_b32 v241, s7, 61
	s_addc_u32 s7, s13, 0
	s_cmp_gt_i32 s55, 15
	v_writelane_b32 v241, s7, 62
	s_cselect_b64 s[10:11], -1, 0
	v_writelane_b32 v241, s10, 63
	s_add_i32 s7, s55, 0x220
	s_nop 0
	v_writelane_b32 v240, s11, 0
	v_writelane_b32 v240, s7, 1
	s_add_i32 s7, s14, -16
	s_cmpk_lt_u32 s55, 0x1f0
	v_writelane_b32 v240, s7, 2
	s_cselect_b64 s[10:11], -1, 0
	v_writelane_b32 v240, s10, 3
	s_cmp_lt_i32 s56, 64
	s_nop 0
	v_writelane_b32 v240, s11, 4
	s_cselect_b64 s[10:11], -1, 0
	s_ashr_i32 s7, s56, 31
	s_lshr_b32 s7, s7, 28
	s_add_i32 s7, s56, s7
	s_ashr_i32 s8, s7, 4
	s_lshl_b32 s8, s8, 2
	s_and_b32 s7, s7, -16
	v_writelane_b32 v240, s10, 5
	s_sub_i32 s7, s56, s7
	s_add_i32 s8, s8, s2
	v_writelane_b32 v240, s11, 6
	s_or_b32 s8, s8, s3
	s_ashr_i32 s7, s7, 2
	v_writelane_b32 v240, s8, 7
	s_cmpk_lt_i32 s55, 0x200
	v_writelane_b32 v240, s7, 8
	s_cselect_b64 s[10:11], -1, 0
	v_writelane_b32 v240, s10, 9
	s_cmp_lt_i32 s56, 16
	s_mul_hi_i32 s7, s56, 0x2e8ba2e9
	v_writelane_b32 v240, s11, 10
	s_cselect_b64 s[10:11], -1, 0
	v_writelane_b32 v240, s10, 11
	s_cmpk_lt_i32 s55, 0x80
	s_nop 0
	v_writelane_b32 v240, s11, 12
	s_cselect_b64 s[10:11], -1, 0
	v_writelane_b32 v240, s10, 13
	s_cmp_lt_i32 s9, 16
	s_nop 0
	v_writelane_b32 v240, s11, 14
	s_cselect_b64 s[10:11], -1, 0
	v_writelane_b32 v240, s10, 15
	s_cmpk_lt_i32 s56, 0x160
	s_nop 0
	v_writelane_b32 v240, s11, 16
	s_cselect_b64 s[10:11], -1, 0
	s_lshr_b32 s8, s7, 31
	s_ashr_i32 s7, s7, 4
	s_add_i32 s7, s7, s8
	s_lshl_b32 s8, s7, 2
	v_writelane_b32 v240, s10, 17
	s_add_i32 s8, s8, s2
	s_or_b32 s2, s8, s3
	v_writelane_b32 v240, s11, 18
	v_writelane_b32 v240, s2, 19
	s_mul_i32 s2, s7, 0xffffffa8
	s_add_i32 s2, s2, s56
	s_ashr_i32 s2, s2, 2
	s_cmpk_lt_i32 s55, 0xb00
	v_writelane_b32 v240, s2, 20
	s_cselect_b64 s[2:3], -1, 0
	v_writelane_b32 v240, s2, 21
	s_cmpk_lt_i32 s56, 0x58
	s_movk_i32 s7, 0x161
	v_writelane_b32 v240, s3, 22
	s_cselect_b64 s[2:3], -1, 0
	v_writelane_b32 v240, s2, 23
	s_cmpk_lt_i32 s55, 0x2c0
	s_nop 0
	v_writelane_b32 v240, s3, 24
	s_cselect_b64 s[2:3], -1, 0
	v_writelane_b32 v240, s2, 25
	s_cmpk_lt_i32 s9, 0x58
	s_nop 0
	v_writelane_b32 v240, s3, 26
	v_writelane_b32 v240, s9, 27
	s_cselect_b64 s[2:3], -1, 0
	s_and_b32 s1, s1, -8
	v_writelane_b32 v240, s2, 28
	s_sub_i32 s1, s55, s1
	s_nop 0
	v_writelane_b32 v240, s3, 29
	s_lshl_b32 s2, s1, 6
	s_cmp_lt_i32 s1, 0
	s_mul_i32 s3, s1, 0x41
	s_cselect_b32 s2, s3, s2
	s_movk_i32 s3, 0xa1
	s_cselect_b32 s3, s3, 0xa0
	s_mul_i32 s3, s1, s3
	s_cselect_b32 s7, s7, 0x160
	s_add_i32 s3, s3, s4
	s_mul_hi_i32 s8, s3, 0x66666667
	s_lshr_b32 s9, s8, 31
	s_ashr_i32 s8, s8, 5
	s_add_i32 s8, s8, s9
	s_mul_i32 s9, s8, 0x50
	s_sub_i32 s3, s3, s9
	s_bfe_i32 s9, s3, 0x80000
	s_bfe_u32 s9, s9, 0x3000c
	s_add_i32 s9, s3, s9
	s_and_b32 s10, s9, 0xf8
	s_sub_i32 s3, s3, s10
	s_lshl_b32 s8, s8, 3
	s_sext_i32_i8 s3, s3
	s_add_i32 s3, s8, s3
	s_add_i32 s2, s2, s4
	s_mul_i32 s1, s1, s7
	v_writelane_b32 v240, s3, 30
	s_ashr_i32 s3, s2, 31
	s_add_i32 s1, s1, s4
	s_lshr_b32 s3, s3, 27
	s_mul_hi_i32 s4, s1, 0x2e8ba2e9
	s_add_i32 s3, s2, s3
	s_lshr_b32 s7, s4, 31
	s_ashr_i32 s4, s4, 5
	s_and_b32 s8, s3, 0xffffffe0
	s_add_i32 s4, s4, s7
	s_sub_i32 s8, s2, s8
	s_mul_i32 s7, s4, 0xb0
	s_bfe_i32 s10, s8, 0x80000
	s_sub_i32 s1, s1, s7
	s_bfe_u32 s10, s10, 0x3000c
	s_sext_i32_i16 s7, s1
; __global__ void __launch_bounds__(NTHR, 2) fwd_megakernel(Args args) {
;     ...
;         { pg8::Gemm g{F.A, wt_ptr(F, l, 0), NB * SEQ, ZS, D}; pg8::StaticOrder S; S.init(NB * SEQ, ZS, F.G, F.bid); S.part(F.px, F.xq, F.rk); pg8::EpiBf16 E{F.Z, ZS}; pg8::gemm_phase(F.lds, F.tid, g, S, E); }
	s_add_i32 s10, s8, s10
	s_bfe_u32 s7, s7, 0x3001c
	s_and_b32 s11, s10, 0xf8
	s_add_i32 s7, s1, s7
	s_sub_i32 s8, s8, s11
	s_and_b32 s11, s7, 0xfff8
	s_sub_i32 s1, s1, s11
	s_lshl_b32 s4, s4, 3
	s_sext_i32_i16 s1, s1
	s_add_i32 s1, s4, s1
	v_writelane_b32 v240, s1, 31
	s_and_b32 s1, s3, 0xffe0
	s_sub_i32 s1, s2, s1
	s_bfe_i32 s2, s1, 0x80000
	s_bfe_u32 s2, s2, 0x3000c
	s_add_i32 s2, s1, s2
	s_and_b32 s4, s2, 0xf8
	s_ashr_i32 s3, s3, 5
	s_sub_i32 s1, s1, s4
	s_lshl_b32 s3, s3, 3
	s_sext_i32_i8 s4, s8
	s_add_i32 s4, s3, s4
	s_sext_i32_i8 s1, s1
	v_writelane_b32 v240, s4, 32
	s_add_i32 s1, s3, s1
	v_writelane_b32 v240, s1, 33
	s_abs_i32 s1, s14
	v_cvt_f32_u32_e32 v0, s1
	s_sub_i32 s3, 0, s1
	s_sext_i32_i16 s7, s7
	s_bfe_i32 s2, s2, 0x80000
	v_rcp_iflag_f32_e32 v0, v0
	s_ashr_i32 s7, s7, 3
	s_sext_i32_i16 s2, s2
	s_ashr_i32 s2, s2, 3
	v_mul_f32_e32 v0, 0x4f7ffffe, v0
	v_cvt_u32_f32_e32 v0, v0
	s_nop 0
	v_readfirstlane_b32 s4, v0
	s_mul_i32 s3, s3, s4
	s_mul_hi_u32 s3, s4, s3
	s_add_i32 s4, s4, s3
	s_abs_i32 s3, s6
	s_mul_hi_u32 s8, s3, s4
	s_mul_i32 s8, s8, s1
	s_sub_i32 s3, s3, s8
	s_bfe_i32 s8, s9, 0x80000
	s_sext_i32_i16 s8, s8
	s_ashr_i32 s8, s8, 3
	v_writelane_b32 v240, s8, 34
	s_bfe_i32 s8, s10, 0x80000
	s_sext_i32_i16 s8, s8
	s_ashr_i32 s8, s8, 3
	v_writelane_b32 v240, s8, 35
	v_writelane_b32 v240, s7, 36
	v_writelane_b32 v240, s2, 37
	s_ashr_i32 s2, s6, 31
	s_sub_i32 s6, s3, s1
	s_cmp_ge_u32 s3, s1
	s_cselect_b32 s3, s6, s3
	s_sub_i32 s6, s3, s1
	s_cmp_ge_u32 s3, s1
	s_cselect_b32 s3, s6, s3
	s_xor_b32 s3, s3, s2
	s_sub_i32 s2, s3, s2
	s_cmpk_lt_i32 s2, 0x410
	v_writelane_b32 v240, s2, 38
	s_cselect_b64 s[2:3], -1, 0
	v_writelane_b32 v240, s2, 39
	v_mov_b32_e32 v0, 0
	v_mov_b32_e32 v145, v0
	v_writelane_b32 v240, s3, 40
	s_abs_i32 s2, s5
	s_mul_hi_u32 s3, s2, s4
	s_mul_i32 s3, s3, s1
	s_sub_i32 s2, s2, s3
	s_ashr_i32 s3, s5, 31
	s_sub_i32 s4, s2, s1
	s_cmp_ge_u32 s2, s1
	s_cselect_b32 s2, s4, s2
	s_sub_i32 s4, s2, s1
	s_cmp_ge_u32 s2, s1
	s_cselect_b32 s1, s4, s2
	s_xor_b32 s1, s1, s3
	s_sub_i32 s1, s1, s3
	s_cmp_lt_i32 s1, 8
	v_writelane_b32 v240, s1, 41
	s_cselect_b64 s[2:3], -1, 0
	v_writelane_b32 v240, s2, 42
	s_add_i32 s0, s0, 32
	s_mov_b64 s[10:11], 0x80
	v_writelane_b32 v240, s3, 43
	v_writelane_b32 v240, s0, 44
	s_mul_i32 s0, s55, 0x2c000
	s_add_i32 s0, s0, 0x21000
	v_writelane_b32 v240, s0, 45
	s_sub_i32 s0, s56, 32
	v_writelane_b32 v240, s0, 46
	s_lshl_b32 s0, s56, 6
	v_writelane_b32 v240, s0, 47
	s_lshl_b32 s0, s55, 6
	v_writelane_b32 v240, s0, 48
	s_lshl_b32 s0, s56, 5
	v_writelane_b32 v240, s0, 49
	s_lshl_b32 s0, s55, 5
	v_writelane_b32 v240, s0, 50
	s_add_i32 s0, 0, 0x20000
	v_writelane_b32 v240, s0, 51
	s_add_i32 s0, 0, 0x20004
	v_writelane_b32 v240, s0, 52
	s_add_i32 s0, 0, 0x4800
	v_writelane_b32 v240, s0, 53
	s_add_i32 s0, 0, 0x9000
	v_writelane_b32 v240, s0, 54
	s_add_i32 s0, 0, 0x20040
	v_writelane_b32 v240, s0, 55
	s_add_i32 s0, 0, 0x1a800
	v_writelane_b32 v240, s0, 56
	s_add_i32 s0, 0, 0x1b800
	v_writelane_b32 v240, s0, 57
	s_add_i32 s0, 0, 0x1b000
	v_writelane_b32 v240, s0, 58
	v_writelane_b32 v240, s34, 59
	s_nop 1
	v_writelane_b32 v240, s35, 60
	v_writelane_b32 v240, s55, 61
	v_writelane_b32 v240, s64, 62
	s_nop 1
	v_writelane_b32 v239, s66, 0
	v_writelane_b32 v239, s67, 1
	v_writelane_b32 v239, s68, 2
	v_writelane_b32 v239, s69, 3
	v_writelane_b32 v239, s70, 4
	v_writelane_b32 v239, s71, 5
	v_writelane_b32 v239, s72, 6
	v_writelane_b32 v239, s73, 7
	v_writelane_b32 v239, s74, 8
	v_writelane_b32 v239, s75, 9
	v_writelane_b32 v239, s76, 10
	v_writelane_b32 v239, s77, 11
	v_writelane_b32 v239, s78, 12
	v_writelane_b32 v239, s79, 13
	v_writelane_b32 v239, s58, 14
	v_writelane_b32 v240, s65, 63
	s_nop 0
	v_writelane_b32 v239, s59, 15
	v_writelane_b32 v239, s56, 16
	v_writelane_b32 v239, s70, 17
	s_nop 1
	v_writelane_b32 v239, s71, 18
	v_writelane_b32 v239, s72, 19
	s_nop 1
	v_writelane_b32 v239, s73, 20
	v_writelane_b32 v239, s74, 21
	s_nop 1
	v_writelane_b32 v239, s75, 22
	v_writelane_b32 v239, s78, 23
	s_nop 1
	v_writelane_b32 v239, s79, 24
	v_writelane_b32 v239, s80, 25
	s_nop 1
	v_writelane_b32 v239, s81, 26
	v_writelane_b32 v239, s82, 27
	s_nop 1
	v_writelane_b32 v239, s83, 28
	v_writelane_b32 v239, s84, 29
	s_nop 1
	v_writelane_b32 v239, s85, 30
	v_writelane_b32 v239, s57, 31
	v_writelane_b32 v239, s86, 32
	s_nop 1
	v_writelane_b32 v239, s87, 33
	v_writelane_b32 v239, s88, 34
	s_nop 1
	v_writelane_b32 v239, s89, 35
	v_writelane_b32 v239, s90, 36
	s_nop 1
	v_writelane_b32 v239, s91, 37
	v_writelane_b32 v239, s92, 38
	s_nop 1
	v_writelane_b32 v239, s93, 39
	v_writelane_b32 v239, s94, 40
	s_nop 1
	v_writelane_b32 v239, s95, 41
	v_writelane_b32 v239, s96, 42
	s_nop 1
	v_writelane_b32 v239, s97, 43
	v_writelane_b32 v239, s54, 44
	s_branch .LBB0_221

; #define LAS __attribute__((address_space(3)))
; __global__ void __launch_bounds__(NTHR, 2) fwd_megakernel(Args args) {
;     ...
;         { unsigned* qctr = (unsigned*)(F.ws + WS_BAR) + XCD_BAR_WORDS + 16 * l; volatile LAS unsigned* qs = (volatile LAS unsigned*)(F.lds + 131072 + 64);
;           for (;;) { __syncthreads(); if (F.tid == 0) qs[0] = atomicAdd(qctr, 1u); __syncthreads(); const int it = (int)qs[0]; if (it >= 512 + 384) break;
;               if (it < 512) attn_item(F, l, it >> 8, (it >> 1) & 127, it & 1, false);
;               else pool_phase(F, l, it - 512, 4096); } }
.LBB0_480:
	s_or_b64 exec, exec, s[6:7]
	v_readlane_b32 s6, v240, 55
	s_waitcnt lgkmcnt(0)
	s_barrier
	v_mov_b32_e32 v1, s6
	ds_read_b32 v1, v1
	s_mov_b64 s[6:7], -1
	s_waitcnt lgkmcnt(0)
	v_readfirstlane_b32 s40, v1
	s_cmpk_gt_i32 s40, 0x42f
	s_cbranch_scc1 .LBB0_475
	s_mov_b64 s[100:101], exec
	v_readlane_b32 s38, v239, 57
	v_readlane_b32 s39, v239, 58
	s_nop 0
	s_and_b64 s[38:39], s[100:101], s[38:39]
	s_mov_b64 exec, s[38:39]
	s_cbranch_execz .Lqpf_next
	v_mov_b32_e32 v235, 1
	v_readlane_b32 s38, v239, 52
	v_readlane_b32 s39, v239, 53
	s_nop 4
	global_atomic_add v234, v0, v235, s[38:39] sc0
